# attention final epilogue through a wave-private f32 LDS image, 16 B/lane row stores, gate/weight loads requested before the exchange barrier
# speedup vs baseline: 1.0095x; 1.0095x over previous
; #define MFMA(a, b, c) __builtin_amdgcn_mfma_f32_32x32x16_bf16((a), (b), (c), 0, 0, 0)
; DI void attn_item(const P& p, int l, int item, char* smem) {
;     ...
;     if (kt >= 0) {
;       const u16* Kc = Ks + (kt & 1) * (256 * 72);
;       const u16* Vc = Kc + 2 * 64 * 72;
;       bf16x8 kf[8];
; #pragma unroll
;       for (int i = 0; i < 8; ++i)
;         kf[i] = *(const bf16x8*)(Kc + (c * 64 + 32 * (i & 1) + li) * 72 + 16 * (i >> 1) + 8 * g);
;       u32x4 vf[16];
; #pragma unroll
;       for (int i = 0; i < 16; ++i) {
;         const int eb = i & 3, s = (i >> 2) & 1, kb = i >> 3;
;         vf[i] = *(const u32x4*)(Vc + (32 * eb + li) * 72 + 32 * kb + 16 * s + 8 * g);
;       }
;       f32x16 S[2];
; #pragma unroll
;       for (int kb = 0; kb < 2; ++kb)
; #pragma unroll
;         for (int r = 0; r < 16; ++r) S[kb][r] = negm;
; #pragma unroll
;       for (int i = 0; i < 8; ++i) S[i & 1] = MFMA(kf[i], qf[i >> 1], S[i & 1]);
;       u32x4 pk[4];
;       float sum = 0.f;
; #pragma unroll
;       for (int ch = 0; ch < 4; ++ch) {
;         const int kb = ch >> 1, s = ch & 1;
; #pragma unroll
;         for (int j2 = 0; j2 < 4; ++j2) {
;           const float p0 = __builtin_amdgcn_exp2f(S[kb][8 * s + 2 * j2]);
;           const float p1 = __builtin_amdgcn_exp2f(S[kb][8 * s + 2 * j2 + 1]);
;           sum += p0 + p1;
;           pk[ch][j2] = pack2(p0, p1);
;         }
;       }
;       ls += sum;
; #pragma unroll
;       for (int i = 0; i < 16; ++i) {
;         const int eb = i & 3, ch = i >> 2;
;         O[eb] = MFMA(__builtin_bit_cast(bf16x8, vf[i]), __builtin_bit_cast(bf16x8, pk[ch]), O[eb]);
;       }
.Lat_exit:
	global_load_dwordx4 v[232:235], v[148:149], off
	global_load_dwordx4 v[228:231], v[156:157], off
	global_load_dwordx4 v[236:239], v[146:147], off
	global_load_dwordx4 v[240:243], v[144:145], off
	v_add_f32_e64 v167, v167, v190
	v_add_f32_e64 v191, v191, v196
	s_nop 0
	v_add_f32_e64 v167, v167, v191
	v_add_u32_e32 v80, 0xd800, v169
	s_waitcnt vmcnt(2)
	ds_write_b128 v168, v[228:231] offset:36864
	ds_write_b128 v168, v[232:235] offset:46080
	s_waitcnt vmcnt(1)
	ds_write2_b64 v80, v[236:237], v[238:239] offset1:2
	v_add_u32_e32 v80, 0xd800, v143
	s_waitcnt vmcnt(0)
	ds_write2_b64 v80, v[240:241], v[242:243] offset1:2
	v_add3_u32 v129, 0, v175, v188
	ds_read_b128 v[80:83], v129
	ds_read_b128 v[130:133], v129 offset:4608
	v_add3_u32 v128, 0, v174, v188
	ds_read_b128 v[134:137], v128 offset:18432
	v_readlane_b32 s6, v248, 5
	s_waitcnt lgkmcnt(2)
	v_mfma_f32_32x32x16_bf16 v[96:111], v[80:83], v[112:115], v[16:31]
	s_waitcnt lgkmcnt(1)
	v_mfma_f32_32x32x16_bf16 v[80:95], v[130:133], v[112:115], v[16:31]
	ds_read_b128 v[130:133], v129 offset:32
	s_waitcnt lgkmcnt(0)
	v_mfma_f32_32x32x16_bf16 v[96:111], v[130:133], v[116:119], v[96:111]
	ds_read_b128 v[130:133], v129 offset:4640
	s_waitcnt lgkmcnt(0)
	v_mfma_f32_32x32x16_bf16 v[80:95], v[130:133], v[116:119], v[80:95]
	ds_read_b128 v[130:133], v129 offset:64
	s_waitcnt lgkmcnt(0)
	v_mfma_f32_32x32x16_bf16 v[96:111], v[130:133], v[124:127], v[96:111]
	ds_read_b128 v[130:133], v129 offset:4672
	s_waitcnt lgkmcnt(0)
	v_mfma_f32_32x32x16_bf16 v[80:95], v[130:133], v[124:127], v[80:95]
	ds_read_b128 v[130:133], v129 offset:96
	s_waitcnt lgkmcnt(0)
	v_mfma_f32_32x32x16_bf16 v[96:111], v[130:133], v[120:123], v[96:111]
	ds_read_b128 v[130:133], v129 offset:4704
	s_nop 10
	v_exp_f32_e32 v144, v100
	v_exp_f32_e32 v145, v101
	v_exp_f32_e32 v146, v102
	v_exp_f32_e32 v147, v103
	ds_read_b128 v[100:103], v128 offset:23040
	v_exp_f32_e32 v138, v96
	v_exp_f32_e32 v139, v97
	v_exp_f32_e32 v142, v98
	v_exp_f32_e32 v143, v99
	v_cvt_pk_bf16_f32 v98, v144, v145
	v_cvt_pk_bf16_f32 v96, v138, v139
	v_cvt_pk_bf16_f32 v99, v146, v147
	v_cvt_pk_bf16_f32 v97, v142, v143
	v_exp_f32_e32 v108, v108
	v_exp_f32_e32 v109, v109
	s_waitcnt lgkmcnt(0)
	v_mfma_f32_32x32x16_bf16 v[48:63], v[100:103], v[96:99], v[48:63]
	ds_read_b128 v[100:103], v128 offset:27648
	v_exp_f32_e32 v110, v110
	v_exp_f32_e32 v111, v111
	v_mfma_f32_32x32x16_bf16 v[80:95], v[130:133], v[120:123], v[80:95]
	s_waitcnt lgkmcnt(0)
	v_mfma_f32_32x32x16_bf16 v[32:47], v[100:103], v[96:99], v[32:47]
	ds_read_b128 v[100:103], v128 offset:32256
	ds_read_b128 v[130:133], v128 offset:18464
	s_nop 7
	v_exp_f32_e32 v148, v84
	v_exp_f32_e32 v149, v85
	v_exp_f32_e32 v150, v86
	v_exp_f32_e32 v151, v87
	v_exp_f32_e32 v152, v88
	v_exp_f32_e32 v153, v89
	s_waitcnt lgkmcnt(1)
	v_mfma_f32_32x32x16_bf16 v[0:15], v[100:103], v[96:99], v[0:15]
	ds_read_b128 v[100:103], v128 offset:23072
	v_exp_f32_e32 v154, v90
	v_exp_f32_e32 v155, v91
	v_exp_f32_e32 v156, v92
	v_exp_f32_e32 v157, v93
	v_exp_f32_e32 v168, v94
	v_exp_f32_e32 v169, v95
	v_mfma_f32_32x32x16_bf16 v[64:79], v[134:137], v[96:99], v[64:79]
	v_exp_f32_e32 v134, v104
	v_exp_f32_e32 v135, v105
	v_exp_f32_e32 v136, v106
	v_exp_f32_e32 v137, v107
	v_cvt_pk_bf16_f32 v98, v108, v109
	v_cvt_pk_bf16_f32 v96, v134, v135
	v_cvt_pk_bf16_f32 v99, v110, v111
	v_cvt_pk_bf16_f32 v97, v136, v137
	v_add_f32_e32 v88, v165, v166
	v_mul_f32_e32 v165, 0x3fb8aa3b, v88
	s_waitcnt lgkmcnt(0)
	v_mfma_f32_32x32x16_bf16 v[48:63], v[100:103], v[96:99], v[48:63]
	ds_read_b128 v[100:103], v128 offset:27680
	v_add_f32_e32 v134, v134, v135
	s_waitcnt lgkmcnt(0)
	v_mfma_f32_32x32x16_bf16 v[32:47], v[100:103], v[96:99], v[32:47]
	ds_read_b128 v[100:103], v128 offset:32288
	ds_read_b128 v[104:107], v128 offset:18496
	ds_read_b128 v[84:87], v128 offset:23104
	v_mfma_f32_32x32x16_bf16 v[64:79], v[130:133], v[96:99], v[64:79]
	v_exp_f32_e32 v130, v80
	v_exp_f32_e32 v131, v81
	v_exp_f32_e32 v132, v82
	v_exp_f32_e32 v133, v83
	v_cvt_pk_bf16_f32 v82, v148, v149
	v_cvt_pk_bf16_f32 v80, v130, v131
	v_cvt_pk_bf16_f32 v83, v150, v151
	v_cvt_pk_bf16_f32 v81, v132, v133
	s_waitcnt lgkmcnt(2)
	v_mfma_f32_32x32x16_bf16 v[0:15], v[100:103], v[96:99], v[0:15]
	s_waitcnt lgkmcnt(0)
	v_mfma_f32_32x32x16_bf16 v[48:63], v[84:87], v[80:83], v[48:63]
	ds_read_b128 v[84:87], v128 offset:27712
	s_waitcnt lgkmcnt(0)
	v_mfma_f32_32x32x16_bf16 v[32:47], v[84:87], v[80:83], v[32:47]
	ds_read_b128 v[84:87], v128 offset:32320
	ds_read_b128 v[96:99], v128 offset:18528
	s_waitcnt lgkmcnt(1)
	v_mfma_f32_32x32x16_bf16 v[0:15], v[84:87], v[80:83], v[0:15]
	ds_read_b128 v[84:87], v128 offset:23136
	v_mfma_f32_32x32x16_bf16 v[64:79], v[104:107], v[80:83], v[64:79]
	v_cvt_pk_bf16_f32 v80, v152, v153
	v_cvt_pk_bf16_f32 v81, v154, v155
	v_cvt_pk_bf16_f32 v82, v156, v157
	v_cvt_pk_bf16_f32 v83, v168, v169
	s_waitcnt lgkmcnt(0)
	s_nop 0
	v_mfma_f32_32x32x16_bf16 v[48:63], v[84:87], v[80:83], v[48:63]
	ds_read_b128 v[84:87], v128 offset:27744
	s_waitcnt lgkmcnt(0)
	v_mfma_f32_32x32x16_bf16 v[32:47], v[84:87], v[80:83], v[32:47]
	ds_read_b128 v[84:87], v128 offset:32352
	s_waitcnt lgkmcnt(0)
	s_barrier
; #define MFMA(a, b, c) __builtin_amdgcn_mfma_f32_32x32x16_bf16((a), (b), (c), 0, 0, 0)
; DI void attn_item(const P& p, int l, int item, char* smem) {
;     ...
;       for (int i = 0; i < 8; ++i) S[i & 1] = MFMA(kf[i], qf[i >> 1], S[i & 1]);
;       u32x4 pk[4];
;       float sum = 0.f;
; #pragma unroll
;       for (int ch = 0; ch < 4; ++ch) {
;         const int kb = ch >> 1, s = ch & 1;
; #pragma unroll
;         for (int j2 = 0; j2 < 4; ++j2) {
;           const float p0 = __builtin_amdgcn_exp2f(S[kb][8 * s + 2 * j2]);
;           const float p1 = __builtin_amdgcn_exp2f(S[kb][8 * s + 2 * j2 + 1]);
;           sum += p0 + p1;
;           pk[ch][j2] = pack2(p0, p1);
;         }
;       }
;       ls += sum;
; #pragma unroll
;       for (int i = 0; i < 16; ++i) {
;         const int eb = i & 3, ch = i >> 2;
;         O[eb] = MFMA(__builtin_bit_cast(bf16x8, vf[i]), __builtin_bit_cast(bf16x8, pk[ch]), O[eb]);
	v_mfma_f32_32x32x16_bf16 v[64:79], v[96:99], v[80:83], v[64:79]
	ds_read_b128 v[96:99], v129 offset:36864
	ds_read_b128 v[100:103], v129 offset:41472
	ds_read_b128 v[104:107], v129 offset:36896
	v_mfma_f32_32x32x16_bf16 v[0:15], v[84:87], v[80:83], v[0:15]
	v_add_f32_e32 v80, v138, v139
	v_add_f32_e32 v80, 0, v80
	v_add_f32_e32 v81, v142, v143
	v_add_f32_e32 v138, v81, v80
	v_exp_f32_e32 v139, v165
	s_waitcnt lgkmcnt(2)
	v_mfma_f32_32x32x16_bf16 v[80:95], v[96:99], v[112:115], v[16:31]
	v_add_f32_e32 v96, v144, v145
	v_add_f32_e32 v96, v96, v138
	v_add_f32_e32 v97, v146, v147
	v_add_f32_e32 v138, v97, v96
	v_add_f32_e32 v134, v134, v138
	ds_read_b128 v[96:99], v129 offset:41504
	s_waitcnt lgkmcnt(2)
	v_mfma_f32_32x32x16_bf16 v[16:31], v[100:103], v[112:115], v[16:31]
	v_add_f32_e32 v100, v136, v137
	v_add_f32_e32 v100, v100, v134
	v_add_f32_e32 v101, v108, v109
	v_add_f32_e32 v100, v101, v100
	v_add_f32_e32 v101, v110, v111
	v_add_f32_e32 v100, v101, v100
	v_add_f32_e32 v101, v130, v131
	v_add_f32_e32 v100, v101, v100
	v_add_f32_e32 v101, v132, v133
	s_waitcnt lgkmcnt(1)
	v_mfma_f32_32x32x16_bf16 v[80:95], v[104:107], v[116:119], v[80:95]
	v_add_f32_e32 v104, v101, v100
	ds_read_b128 v[100:103], v129 offset:36928
	v_add_f32_e32 v105, v148, v149
	v_add_f32_e32 v104, v105, v104
	v_add_f32_e32 v105, v150, v151
	v_add_f32_e32 v108, v105, v104
	v_add_f32_e32 v109, v152, v153
	s_waitcnt lgkmcnt(0)
	v_mfma_f32_32x32x16_bf16 v[80:95], v[100:103], v[124:127], v[80:95]
	v_add_f32_e32 v110, v154, v155
	v_add_f32_e32 v100, v109, v108
	v_add_f32_e32 v111, v156, v157
	v_add_f32_e32 v100, v110, v100
	v_add_f32_e32 v112, v168, v169
	v_add_f32_e32 v100, v111, v100
	v_add_f32_e32 v108, v112, v100
	v_mfma_f32_32x32x16_bf16 v[16:31], v[96:99], v[116:119], v[16:31]
	ds_read_b128 v[96:99], v129 offset:41536
	ds_read_b128 v[104:107], v129 offset:36960
	ds_read_b128 v[100:103], v129 offset:41568
	v_add_f32_e32 v129, v167, v108
	v_add_f32_e32 v108, v163, v164
	v_mul_f32_e32 v138, 0x3fb8aa3b, v108
	v_add_u32_e32 v150, 0xd800, v128
	s_waitcnt lgkmcnt(1)
	v_mfma_f32_32x32x16_bf16 v[80:95], v[104:107], v[120:123], v[80:95]
	v_mfma_f32_32x32x16_bf16 v[16:31], v[96:99], v[124:127], v[16:31]
	s_nop 10
	v_exp_f32_e32 v154, v80
	v_exp_f32_e32 v155, v81
	v_exp_f32_e32 v156, v82
	v_exp_f32_e32 v157, v83
	v_exp_f32_e32 v163, v84
	v_exp_f32_e32 v164, v85
	v_exp_f32_e32 v165, v86
	v_exp_f32_e32 v166, v87
	ds_read_b128 v[96:99], v128 offset:55296
	ds_read_b128 v[108:111], v128 offset:55328
	ds_read_b128 v[112:115], v128 offset:59904
	ds_read_b128 v[116:119], v128 offset:59936
	s_waitcnt lgkmcnt(4)
	v_mfma_f32_32x32x16_bf16 v[16:31], v[100:103], v[120:123], v[16:31]
	ds_read_b128 v[84:87], v128 offset:64512
	ds_read_b128 v[100:103], v128 offset:64544
	v_cvt_pk_bf16_f32 v80, v154, v155
	v_cvt_pk_bf16_f32 v81, v156, v157
	v_cvt_pk_bf16_f32 v82, v163, v164
	v_cvt_pk_bf16_f32 v83, v165, v166
	s_nop 5
	v_exp_f32_e32 v16, v16
	s_waitcnt lgkmcnt(5)
	v_mfma_f32_32x32x16_bf16 v[64:79], v[96:99], v[80:83], v[64:79]
	ds_read_b128 v[96:99], v150 offset:13824
	ds_read_b128 v[104:107], v150 offset:13856
	ds_read_b128 v[120:123], v128 offset:55360
	ds_read_b128 v[124:127], v128 offset:55392
	ds_read_b128 v[130:133], v128 offset:59968
	ds_read_b128 v[134:137], v128 offset:60000
	ds_read_b128 v[142:145], v128 offset:64576
	v_exp_f32_e32 v17, v17
	v_exp_f32_e32 v18, v18
	v_exp_f32_e32 v19, v19
	v_exp_f32_e32 v20, v20
	v_exp_f32_e32 v21, v21
	v_exp_f32_e32 v22, v22
	s_waitcnt lgkmcnt(10)
	v_mfma_f32_32x32x16_bf16 v[48:63], v[112:115], v[80:83], v[48:63]
	ds_read_b128 v[112:115], v128 offset:64608
	ds_read_b128 v[146:149], v150 offset:13888
	ds_read_b128 v[150:153], v150 offset:13920
	v_add_f32_e32 v128, v154, v155
	v_add_f32_e32 v128, 0, v128
	v_add_f32_e32 v154, v156, v157
	v_add_f32_e32 v128, v154, v128
	v_exp_f32_e32 v23, v23
	s_waitcnt lgkmcnt(0)
	v_mfma_f32_32x32x16_bf16 v[32:47], v[84:87], v[80:83], v[32:47]
	v_exp_f32_e32 v85, v88
	v_exp_f32_e32 v86, v89
	v_exp_f32_e32 v87, v90
	v_exp_f32_e32 v88, v91
	v_add_f32_e32 v84, v163, v164
	v_exp_f32_e32 v89, v92
	v_exp_f32_e32 v90, v93
	v_add_f32_e32 v84, v84, v128
	v_mfma_f32_32x32x16_bf16 v[0:15], v[96:99], v[80:83], v[0:15]
	v_exp_f32_e32 v91, v94
	v_exp_f32_e32 v92, v95
	v_add_f32_e32 v93, v165, v166
	v_cvt_pk_bf16_f32 v80, v85, v86
	v_add_f32_e32 v84, v93, v84
	v_add_f32_e32 v85, v85, v86
	v_add_f32_e32 v84, v85, v84
	v_add_f32_e32 v85, v87, v88
	v_add_f32_e32 v84, v85, v84
	v_add_f32_e32 v85, v89, v90
	v_add_f32_e32 v84, v85, v84
	v_add_f32_e32 v85, v91, v92
	v_add_f32_e32 v84, v85, v84
	v_add_f32_e32 v85, v16, v17
	v_add_f32_e32 v84, v85, v84
	v_cvt_pk_bf16_f32 v16, v16, v17
	v_add_f32_e32 v17, v18, v19
	v_cvt_pk_bf16_f32 v81, v87, v88
	v_cvt_pk_bf16_f32 v82, v89, v90
	v_cvt_pk_bf16_f32 v83, v91, v92
	v_add_f32_e32 v84, v17, v84
	v_cvt_pk_bf16_f32 v17, v18, v19
	v_add_f32_e32 v18, v20, v21
	v_mfma_f32_32x32x16_bf16 v[64:79], v[108:111], v[80:83], v[64:79]
	v_cvt_pk_bf16_f32 v19, v22, v23
	s_barrier
; DI void attn_item(const P& p, int l, int item, char* smem) {
;     ...
;   const float lt = ls + __shfl_xor(ls, 32);
;   const float inv = (c == 0) ? (1.0f / lt) : (lam / lt);
;   float* exch = (float*)smem + qg * (64 * 64);
;   if (c == 1) {
; #pragma unroll
;     for (int eb = 0; eb < 4; ++eb)
; #pragma unroll
;       for (int r = 0; r < 16; ++r) exch[(eb * 16 + r) * 64 + lane] = O[eb][r] * inv;
;   }
;     ...
;     const size_t tok = (size_t)b * SEQ + tq;
; #pragma unroll
;     for (int eb = 0; eb < 4; ++eb)
; #pragma unroll
;       for (int rq = 0; rq < 4; ++rq) {
;         const int e = 32 * eb + 8 * rq + 4 * g;
;         const uint2 gt = *(const uint2*)(p.AG + tok * 512 + h * 128 + e);
;         const float4 sg = *(const float4*)(p.subg + l * 128 + e);
	v_mfma_f32_32x32x16_bf16 v[48:63], v[116:119], v[80:83], v[48:63]
	v_mfma_f32_32x32x16_bf16 v[32:47], v[100:103], v[80:83], v[32:47]
	v_mfma_f32_32x32x16_bf16 v[0:15], v[104:107], v[80:83], v[0:15]
	v_add_f32_e32 v80, v18, v84
	v_cvt_pk_bf16_f32 v18, v20, v21
	v_add_f32_e32 v20, v22, v23
	v_exp_f32_e32 v21, v24
	v_exp_f32_e32 v22, v25
	v_exp_f32_e32 v23, v26
	v_exp_f32_e32 v25, v27
	v_add_f32_e32 v24, v20, v80
	v_add_f32_e32 v26, v21, v22
	v_cvt_pk_bf16_f32 v20, v21, v22
	v_add_f32_e32 v27, v23, v25
	v_cvt_pk_bf16_f32 v21, v23, v25
	v_exp_f32_e32 v22, v28
	v_exp_f32_e32 v23, v29
	v_exp_f32_e32 v25, v30
	v_exp_f32_e32 v28, v31
	v_add_f32_e32 v24, v26, v24
	v_add_f32_e32 v29, v22, v23
	v_add_f32_e32 v24, v27, v24
	v_add_f32_e32 v30, v25, v28
	v_add_f32_e32 v24, v29, v24
	v_mfma_f32_32x32x16_bf16 v[64:79], v[120:123], v[16:19], v[64:79]
	v_cvt_pk_bf16_f32 v22, v22, v23
	v_cvt_pk_bf16_f32 v23, v25, v28
	v_mfma_f32_32x32x16_bf16 v[48:63], v[130:133], v[16:19], v[48:63]
	v_mfma_f32_32x32x16_bf16 v[32:47], v[142:145], v[16:19], v[32:47]
	v_mfma_f32_32x32x16_bf16 v[0:15], v[146:149], v[16:19], v[0:15]
	v_add_f32_e32 v16, v30, v24
	v_exp_f32_e32 v17, v138
	v_add_f32_e32 v16, v129, v16
	ds_bpermute_b32 v18, v158, v16
	v_sub_f32_e32 v17, v17, v139
	v_add_f32_e32 v17, s6, v17
	s_movk_i32 s6, 0x100
	v_cmp_gt_u32_e64 s[6:7], s6, v161
	s_waitcnt lgkmcnt(0)
	v_add_f32_e32 v16, v16, v18
	v_mfma_f32_32x32x16_bf16 v[64:79], v[124:127], v[20:23], v[64:79]
	v_cndmask_b32_e64 v17, v17, 1.0, s[6:7]
	v_div_scale_f32 v18, s[10:11], v16, v16, v17
	v_rcp_f32_e32 v19, v18
	s_nop 0
	v_fma_f32 v24, -v18, v19, 1.0
	v_mfma_f32_32x32x16_bf16 v[48:63], v[134:137], v[20:23], v[48:63]
	v_fmac_f32_e32 v19, v24, v19
	v_div_scale_f32 v24, vcc, v17, v16, v17
	v_mul_f32_e32 v25, v24, v19
	v_fma_f32 v26, -v18, v25, v24
	v_fmac_f32_e32 v25, v26, v19
	v_fma_f32 v18, -v18, v25, v24
	v_mfma_f32_32x32x16_bf16 v[32:47], v[112:115], v[20:23], v[32:47]
	v_div_fmas_f32 v18, v18, v19, v25
	v_div_fixup_f32 v80, v18, v16, v17
	v_lshl_add_u32 v16, v162, 14, 0
	v_cmp_eq_u32_e32 vcc, 1, v160
	v_lshl_add_u32 v18, v141, 2, v16
	v_mfma_f32_32x32x16_bf16 v[0:15], v[150:153], v[20:23], v[0:15]
	s_and_saveexec_b64 s[10:11], s[6:7]
	s_cbranch_execz .Lfin_nl
	v_and_b32_e32 v142, 15, v161
	v_bfe_u32 v143, v161, 4, 2
	v_and_b32_e32 v144, 0xffffffe0, v140
	v_add_u32_e32 v144, v144, v143
	s_lshl_b32 s56, s12, 11
	s_and_b32 s56, s56, 0x2000
	v_add_u32_e32 v144, s56, v144
	v_lshlrev_b32_e32 v144, 10, v144
	s_lshl_b32 s56, s95, 8
	s_and_b32 s56, s56, 0x300
	v_add_u32_e32 v144, s56, v144
	v_lshl_add_u32 v144, v142, 4, v144
	v_mov_b32_e32 v147, v144
	v_lshlrev_b32_e32 v145, 5, v142
	global_load_dwordx4 v[100:103], v145, s[30:31]
	global_load_dwordx4 v[104:107], v145, s[30:31] offset:16
	global_load_dwordx4 v[228:231], v144, s[44:45]
	v_add_u32_e32 v144, 0x1000, v144
	global_load_dwordx4 v[232:235], v144, s[44:45]
	v_add_u32_e32 v144, 0x1000, v144
	global_load_dwordx4 v[236:239], v144, s[44:45]
	v_add_u32_e32 v144, 0x1000, v144
	global_load_dwordx4 v[240:243], v144, s[44:45]
	v_add_u32_e32 v144, 0x1000, v144
	global_load_dwordx4 v[84:87], v144, s[44:45]
	v_add_u32_e32 v144, 0x1000, v144
	global_load_dwordx4 v[88:91], v144, s[44:45]
	v_add_u32_e32 v144, 0x1000, v144
	global_load_dwordx4 v[92:95], v144, s[44:45]
	v_add_u32_e32 v144, 0x1000, v144
	global_load_dwordx4 v[96:99], v144, s[44:45]
.Lfin_nl:
	s_or_b64 exec, exec, s[10:11]
	s_and_saveexec_b64 s[10:11], vcc
	s_cbranch_execz .LBB0_469
	v_mul_f32_e32 v16, v64, v80
	v_mul_f32_e32 v17, v65, v80
	ds_write2st64_b32 v18, v16, v17 offset1:1
	v_mul_f32_e32 v16, v66, v80
	v_mul_f32_e32 v17, v67, v80
	ds_write2st64_b32 v18, v16, v17 offset0:2 offset1:3
	v_mul_f32_e32 v16, v68, v80
	v_mul_f32_e32 v17, v69, v80
	ds_write2st64_b32 v18, v16, v17 offset0:4 offset1:5
	v_mul_f32_e32 v16, v70, v80
	v_mul_f32_e32 v17, v71, v80
	ds_write2st64_b32 v18, v16, v17 offset0:6 offset1:7
	v_mul_f32_e32 v16, v72, v80
	v_mul_f32_e32 v17, v73, v80
	ds_write2st64_b32 v18, v16, v17 offset0:8 offset1:9
	v_mul_f32_e32 v16, v74, v80
	v_mul_f32_e32 v17, v75, v80
	ds_write2st64_b32 v18, v16, v17 offset0:10 offset1:11
	v_mul_f32_e32 v16, v76, v80
	v_mul_f32_e32 v17, v77, v80
	ds_write2st64_b32 v18, v16, v17 offset0:12 offset1:13
	v_mul_f32_e32 v16, v78, v80
	v_mul_f32_e32 v17, v79, v80
	ds_write2st64_b32 v18, v16, v17 offset0:14 offset1:15
	v_mul_f32_e32 v16, v48, v80
	v_mul_f32_e32 v17, v49, v80
	ds_write2st64_b32 v18, v16, v17 offset0:16 offset1:17
	v_mul_f32_e32 v16, v50, v80
	v_mul_f32_e32 v17, v51, v80
	ds_write2st64_b32 v18, v16, v17 offset0:18 offset1:19
	v_mul_f32_e32 v16, v52, v80
	v_mul_f32_e32 v17, v53, v80
	ds_write2st64_b32 v18, v16, v17 offset0:20 offset1:21
	v_mul_f32_e32 v16, v54, v80
	v_mul_f32_e32 v17, v55, v80
	ds_write2st64_b32 v18, v16, v17 offset0:22 offset1:23
	v_mul_f32_e32 v16, v56, v80
	v_mul_f32_e32 v17, v57, v80
	ds_write2st64_b32 v18, v16, v17 offset0:24 offset1:25
	v_mul_f32_e32 v16, v58, v80
	v_mul_f32_e32 v17, v59, v80
	ds_write2st64_b32 v18, v16, v17 offset0:26 offset1:27
	v_mul_f32_e32 v16, v60, v80
	v_mul_f32_e32 v17, v61, v80
	ds_write2st64_b32 v18, v16, v17 offset0:28 offset1:29
	v_mul_f32_e32 v16, v62, v80
	v_mul_f32_e32 v17, v63, v80
	ds_write2st64_b32 v18, v16, v17 offset0:30 offset1:31
	v_mul_f32_e32 v16, v32, v80
	v_mul_f32_e32 v17, v33, v80
	ds_write2st64_b32 v18, v16, v17 offset0:32 offset1:33
	v_mul_f32_e32 v16, v34, v80
	v_mul_f32_e32 v17, v35, v80
	ds_write2st64_b32 v18, v16, v17 offset0:34 offset1:35
	v_mul_f32_e32 v16, v36, v80
	v_mul_f32_e32 v17, v37, v80
	ds_write2st64_b32 v18, v16, v17 offset0:36 offset1:37
	v_mul_f32_e32 v16, v38, v80
; DI void attn_item(const P& p, int l, int item, char* smem) {
;     ...
;   if (c == 1) {
; #pragma unroll
;     for (int eb = 0; eb < 4; ++eb)
; #pragma unroll
;       for (int r = 0; r < 16; ++r) exch[(eb * 16 + r) * 64 + lane] = O[eb][r] * inv;
;   }
;   __syncthreads();
;   if (c == 0) {
;     float ss = 0.f;
; #pragma unroll
;     for (int eb = 0; eb < 4; ++eb)
; #pragma unroll
;       for (int r = 0; r < 16; ++r) {
;         const float o = O[eb][r] * inv - exch[(eb * 16 + r) * 64 + lane];
;         O[eb][r] = o;
;         ss += o * o;
;       }
;     ss += __shfl_xor(ss, 32);
	v_mul_f32_e32 v17, v39, v80
	ds_write2st64_b32 v18, v16, v17 offset0:38 offset1:39
	v_mul_f32_e32 v16, v40, v80
	v_mul_f32_e32 v17, v41, v80
	ds_write2st64_b32 v18, v16, v17 offset0:40 offset1:41
	v_mul_f32_e32 v16, v42, v80
	v_mul_f32_e32 v17, v43, v80
	ds_write2st64_b32 v18, v16, v17 offset0:42 offset1:43
	v_mul_f32_e32 v16, v44, v80
	v_mul_f32_e32 v17, v45, v80
	ds_write2st64_b32 v18, v16, v17 offset0:44 offset1:45
	v_mul_f32_e32 v16, v46, v80
	v_mul_f32_e32 v17, v47, v80
	ds_write2st64_b32 v18, v16, v17 offset0:46 offset1:47
	v_mul_f32_e32 v16, v0, v80
	v_mul_f32_e32 v17, v1, v80
	ds_write2st64_b32 v18, v16, v17 offset0:48 offset1:49
	v_mul_f32_e32 v16, v2, v80
	v_mul_f32_e32 v17, v3, v80
	ds_write2st64_b32 v18, v16, v17 offset0:50 offset1:51
	v_mul_f32_e32 v16, v4, v80
	v_mul_f32_e32 v17, v5, v80
	ds_write2st64_b32 v18, v16, v17 offset0:52 offset1:53
	v_mul_f32_e32 v16, v6, v80
	v_mul_f32_e32 v17, v7, v80
	ds_write2st64_b32 v18, v16, v17 offset0:54 offset1:55
	v_mul_f32_e32 v16, v8, v80
	v_mul_f32_e32 v17, v9, v80
	ds_write2st64_b32 v18, v16, v17 offset0:56 offset1:57
	v_mul_f32_e32 v16, v10, v80
	v_mul_f32_e32 v17, v11, v80
	ds_write2st64_b32 v18, v16, v17 offset0:58 offset1:59
	v_mul_f32_e32 v16, v12, v80
	v_mul_f32_e32 v17, v13, v80
	ds_write2st64_b32 v18, v16, v17 offset0:60 offset1:61
	v_mul_f32_e32 v16, v14, v80
	v_mul_f32_e32 v17, v15, v80
	ds_write2st64_b32 v18, v16, v17 offset0:62 offset1:63
.LBB0_469:
	s_or_b64 exec, exec, s[10:11]
	s_waitcnt lgkmcnt(0)
	s_barrier
	s_and_saveexec_b64 s[10:11], s[6:7]
	s_cbranch_execz .LBB0_471
	ds_read2st64_b32 v[108:109], v18 offset0:0 offset1:1
	ds_read2st64_b32 v[110:111], v18 offset0:2 offset1:3
	ds_read2st64_b32 v[112:113], v18 offset0:4 offset1:5
	ds_read2st64_b32 v[114:115], v18 offset0:6 offset1:7
	ds_read2st64_b32 v[116:117], v18 offset0:8 offset1:9
	ds_read2st64_b32 v[118:119], v18 offset0:10 offset1:11
	ds_read2st64_b32 v[120:121], v18 offset0:12 offset1:13
	ds_read2st64_b32 v[122:123], v18 offset0:14 offset1:15
	ds_read2st64_b32 v[124:125], v18 offset0:16 offset1:17
	ds_read2st64_b32 v[126:127], v18 offset0:18 offset1:19
	ds_read2st64_b32 v[128:129], v18 offset0:20 offset1:21
	ds_read2st64_b32 v[130:131], v18 offset0:22 offset1:23
	ds_read2st64_b32 v[132:133], v18 offset0:24 offset1:25
	ds_read2st64_b32 v[134:135], v18 offset0:26 offset1:27
	ds_read2st64_b32 v[136:137], v18 offset0:28 offset1:29
	ds_read2st64_b32 v[138:139], v18 offset0:30 offset1:31
	v_mov_b32_e32 v146, 0x4200
	v_mul_u32_u24_e32 v146, v162, v146
	v_add_u32_e32 v146, 0x12000, v146
	v_mov_b32_e32 v148, 0x210
	v_and_b32_e32 v149, 31, v161
	v_mad_u32_u24 v149, v149, v148, v146
	v_add_u32_e32 v149, v149, v188
	v_mad_u32_u24 v146, v143, v148, v146
	v_lshl_add_u32 v146, v142, 5, v146
	s_waitcnt lgkmcnt(15)
	v_pk_fma_f32 v[64:65], v[64:65], v[80:81], v[108:109] op_sel_hi:[1,0,1] neg_lo:[0,0,1] neg_hi:[0,0,1]
	ds_read2st64_b32 v[108:109], v18 offset0:32 offset1:33
	s_waitcnt lgkmcnt(15)
	v_pk_fma_f32 v[66:67], v[66:67], v[80:81], v[110:111] op_sel_hi:[1,0,1] neg_lo:[0,0,1] neg_hi:[0,0,1]
	ds_read2st64_b32 v[110:111], v18 offset0:34 offset1:35
	s_waitcnt lgkmcnt(15)
	v_pk_fma_f32 v[68:69], v[68:69], v[80:81], v[112:113] op_sel_hi:[1,0,1] neg_lo:[0,0,1] neg_hi:[0,0,1]
	ds_read2st64_b32 v[112:113], v18 offset0:36 offset1:37
	s_waitcnt lgkmcnt(15)
	v_pk_fma_f32 v[70:71], v[70:71], v[80:81], v[114:115] op_sel_hi:[1,0,1] neg_lo:[0,0,1] neg_hi:[0,0,1]
	ds_read2st64_b32 v[114:115], v18 offset0:38 offset1:39
	s_waitcnt lgkmcnt(15)
	v_pk_fma_f32 v[72:73], v[72:73], v[80:81], v[116:117] op_sel_hi:[1,0,1] neg_lo:[0,0,1] neg_hi:[0,0,1]
	ds_read2st64_b32 v[116:117], v18 offset0:40 offset1:41
	s_waitcnt lgkmcnt(15)
	v_pk_fma_f32 v[74:75], v[74:75], v[80:81], v[118:119] op_sel_hi:[1,0,1] neg_lo:[0,0,1] neg_hi:[0,0,1]
	ds_read2st64_b32 v[118:119], v18 offset0:42 offset1:43
	s_waitcnt lgkmcnt(15)
	v_pk_fma_f32 v[76:77], v[76:77], v[80:81], v[120:121] op_sel_hi:[1,0,1] neg_lo:[0,0,1] neg_hi:[0,0,1]
	ds_read2st64_b32 v[120:121], v18 offset0:44 offset1:45
	s_waitcnt lgkmcnt(15)
	v_pk_fma_f32 v[78:79], v[78:79], v[80:81], v[122:123] op_sel_hi:[1,0,1] neg_lo:[0,0,1] neg_hi:[0,0,1]
	ds_read2st64_b32 v[122:123], v18 offset0:46 offset1:47
	s_waitcnt lgkmcnt(15)
	v_pk_fma_f32 v[48:49], v[48:49], v[80:81], v[124:125] op_sel_hi:[1,0,1] neg_lo:[0,0,1] neg_hi:[0,0,1]
	ds_read2st64_b32 v[124:125], v18 offset0:48 offset1:49
	s_waitcnt lgkmcnt(15)
	v_pk_fma_f32 v[50:51], v[50:51], v[80:81], v[126:127] op_sel_hi:[1,0,1] neg_lo:[0,0,1] neg_hi:[0,0,1]
	ds_read2st64_b32 v[126:127], v18 offset0:50 offset1:51
	s_waitcnt lgkmcnt(15)
	v_pk_fma_f32 v[52:53], v[52:53], v[80:81], v[128:129] op_sel_hi:[1,0,1] neg_lo:[0,0,1] neg_hi:[0,0,1]
	ds_read2st64_b32 v[128:129], v18 offset0:52 offset1:53
	s_waitcnt lgkmcnt(15)
	v_pk_fma_f32 v[54:55], v[54:55], v[80:81], v[130:131] op_sel_hi:[1,0,1] neg_lo:[0,0,1] neg_hi:[0,0,1]
	ds_read2st64_b32 v[130:131], v18 offset0:54 offset1:55
	s_waitcnt lgkmcnt(15)
	v_pk_fma_f32 v[56:57], v[56:57], v[80:81], v[132:133] op_sel_hi:[1,0,1] neg_lo:[0,0,1] neg_hi:[0,0,1]
	ds_read2st64_b32 v[132:133], v18 offset0:56 offset1:57
	s_waitcnt lgkmcnt(15)
	v_pk_fma_f32 v[58:59], v[58:59], v[80:81], v[134:135] op_sel_hi:[1,0,1] neg_lo:[0,0,1] neg_hi:[0,0,1]
	ds_read2st64_b32 v[134:135], v18 offset0:58 offset1:59
	s_waitcnt lgkmcnt(15)
	v_pk_fma_f32 v[60:61], v[60:61], v[80:81], v[136:137] op_sel_hi:[1,0,1] neg_lo:[0,0,1] neg_hi:[0,0,1]
	ds_read2st64_b32 v[136:137], v18 offset0:60 offset1:61
	s_waitcnt lgkmcnt(15)
	v_pk_fma_f32 v[62:63], v[62:63], v[80:81], v[138:139] op_sel_hi:[1,0,1] neg_lo:[0,0,1] neg_hi:[0,0,1]
	ds_read2st64_b32 v[138:139], v18 offset0:62 offset1:63
	s_waitcnt lgkmcnt(15)
; DI void attn_item(const P& p, int l, int item, char* smem) {
;     ...
;   if (c == 0) {
;     float ss = 0.f;
; #pragma unroll
;     for (int eb = 0; eb < 4; ++eb)
; #pragma unroll
;       for (int r = 0; r < 16; ++r) {
;         const float o = O[eb][r] * inv - exch[(eb * 16 + r) * 64 + lane];
;         O[eb][r] = o;
;         ss += o * o;
;       }
;     ss += __shfl_xor(ss, 32);
	v_pk_fma_f32 v[32:33], v[32:33], v[80:81], v[108:109] op_sel_hi:[1,0,1] neg_lo:[0,0,1] neg_hi:[0,0,1]
	s_waitcnt lgkmcnt(14)
	v_pk_fma_f32 v[34:35], v[34:35], v[80:81], v[110:111] op_sel_hi:[1,0,1] neg_lo:[0,0,1] neg_hi:[0,0,1]
	s_waitcnt lgkmcnt(13)
	v_pk_fma_f32 v[36:37], v[36:37], v[80:81], v[112:113] op_sel_hi:[1,0,1] neg_lo:[0,0,1] neg_hi:[0,0,1]
	s_waitcnt lgkmcnt(12)
	v_pk_fma_f32 v[38:39], v[38:39], v[80:81], v[114:115] op_sel_hi:[1,0,1] neg_lo:[0,0,1] neg_hi:[0,0,1]
	s_waitcnt lgkmcnt(11)
	v_pk_fma_f32 v[40:41], v[40:41], v[80:81], v[116:117] op_sel_hi:[1,0,1] neg_lo:[0,0,1] neg_hi:[0,0,1]
	s_waitcnt lgkmcnt(10)
	v_pk_fma_f32 v[42:43], v[42:43], v[80:81], v[118:119] op_sel_hi:[1,0,1] neg_lo:[0,0,1] neg_hi:[0,0,1]
	s_waitcnt lgkmcnt(9)
	v_pk_fma_f32 v[44:45], v[44:45], v[80:81], v[120:121] op_sel_hi:[1,0,1] neg_lo:[0,0,1] neg_hi:[0,0,1]
	s_waitcnt lgkmcnt(8)
	v_pk_fma_f32 v[46:47], v[46:47], v[80:81], v[122:123] op_sel_hi:[1,0,1] neg_lo:[0,0,1] neg_hi:[0,0,1]
	s_waitcnt lgkmcnt(7)
	v_pk_fma_f32 v[0:1], v[0:1], v[80:81], v[124:125] op_sel_hi:[1,0,1] neg_lo:[0,0,1] neg_hi:[0,0,1]
	s_waitcnt lgkmcnt(6)
	v_pk_fma_f32 v[2:3], v[2:3], v[80:81], v[126:127] op_sel_hi:[1,0,1] neg_lo:[0,0,1] neg_hi:[0,0,1]
	s_waitcnt lgkmcnt(5)
	v_pk_fma_f32 v[4:5], v[4:5], v[80:81], v[128:129] op_sel_hi:[1,0,1] neg_lo:[0,0,1] neg_hi:[0,0,1]
	s_waitcnt lgkmcnt(4)
	v_pk_fma_f32 v[6:7], v[6:7], v[80:81], v[130:131] op_sel_hi:[1,0,1] neg_lo:[0,0,1] neg_hi:[0,0,1]
	s_waitcnt lgkmcnt(3)
	v_pk_fma_f32 v[8:9], v[8:9], v[80:81], v[132:133] op_sel_hi:[1,0,1] neg_lo:[0,0,1] neg_hi:[0,0,1]
	s_waitcnt lgkmcnt(2)
	v_pk_fma_f32 v[10:11], v[10:11], v[80:81], v[134:135] op_sel_hi:[1,0,1] neg_lo:[0,0,1] neg_hi:[0,0,1]
	s_waitcnt lgkmcnt(1)
	v_pk_fma_f32 v[12:13], v[12:13], v[80:81], v[136:137] op_sel_hi:[1,0,1] neg_lo:[0,0,1] neg_hi:[0,0,1]
	s_waitcnt lgkmcnt(0)
	v_pk_fma_f32 v[14:15], v[14:15], v[80:81], v[138:139] op_sel_hi:[1,0,1] neg_lo:[0,0,1] neg_hi:[0,0,1]
	v_pk_mul_f32 v[150:151], v[64:65], v[64:65]
	v_pk_mul_f32 v[152:153], v[66:67], v[66:67]
	v_add_f32_e32 v80, v150, v151
	v_add_f32_e32 v80, v80, v152
	v_add_f32_e32 v80, v80, v153
	v_pk_mul_f32 v[150:151], v[68:69], v[68:69]
	v_add_f32_e32 v80, v80, v150
	v_add_f32_e32 v80, v80, v151
	v_pk_mul_f32 v[152:153], v[70:71], v[70:71]
	v_add_f32_e32 v80, v80, v152
	v_add_f32_e32 v80, v80, v153
	v_pk_mul_f32 v[150:151], v[72:73], v[72:73]
	v_add_f32_e32 v80, v80, v150
	v_add_f32_e32 v80, v80, v151
	v_pk_mul_f32 v[152:153], v[74:75], v[74:75]
	v_add_f32_e32 v80, v80, v152
	v_add_f32_e32 v80, v80, v153
	v_pk_mul_f32 v[150:151], v[76:77], v[76:77]
	v_add_f32_e32 v80, v80, v150
	v_add_f32_e32 v80, v80, v151
	v_pk_mul_f32 v[152:153], v[78:79], v[78:79]
	v_add_f32_e32 v80, v80, v152
	v_add_f32_e32 v80, v80, v153
	v_pk_mul_f32 v[150:151], v[48:49], v[48:49]
	v_add_f32_e32 v80, v80, v150
	v_add_f32_e32 v80, v80, v151
	v_pk_mul_f32 v[152:153], v[50:51], v[50:51]
	v_add_f32_e32 v80, v80, v152
	v_add_f32_e32 v80, v80, v153
	v_pk_mul_f32 v[150:151], v[52:53], v[52:53]
	v_add_f32_e32 v80, v80, v150
	v_add_f32_e32 v80, v80, v151
	v_pk_mul_f32 v[152:153], v[54:55], v[54:55]
	v_add_f32_e32 v80, v80, v152
	v_add_f32_e32 v80, v80, v153
	v_pk_mul_f32 v[150:151], v[56:57], v[56:57]
	v_add_f32_e32 v80, v80, v150
	v_add_f32_e32 v80, v80, v151
	v_pk_mul_f32 v[152:153], v[58:59], v[58:59]
	v_add_f32_e32 v80, v80, v152
	v_add_f32_e32 v80, v80, v153
	v_pk_mul_f32 v[150:151], v[60:61], v[60:61]
	v_add_f32_e32 v80, v80, v150
	v_add_f32_e32 v80, v80, v151
	v_pk_mul_f32 v[152:153], v[62:63], v[62:63]
	v_add_f32_e32 v80, v80, v152
	v_add_f32_e32 v80, v80, v153
	v_pk_mul_f32 v[150:151], v[32:33], v[32:33]
	v_add_f32_e32 v80, v80, v150
	v_add_f32_e32 v80, v80, v151
	v_pk_mul_f32 v[152:153], v[34:35], v[34:35]
	v_add_f32_e32 v80, v80, v152
	v_add_f32_e32 v80, v80, v153
	v_pk_mul_f32 v[150:151], v[36:37], v[36:37]
	v_add_f32_e32 v80, v80, v150
	v_add_f32_e32 v80, v80, v151
	v_pk_mul_f32 v[152:153], v[38:39], v[38:39]
	v_add_f32_e32 v80, v80, v152
	v_add_f32_e32 v80, v80, v153
	v_pk_mul_f32 v[150:151], v[40:41], v[40:41]
	v_add_f32_e32 v80, v80, v150
	v_add_f32_e32 v80, v80, v151
	v_pk_mul_f32 v[152:153], v[42:43], v[42:43]
	v_add_f32_e32 v80, v80, v152
	v_add_f32_e32 v80, v80, v153
	v_pk_mul_f32 v[150:151], v[44:45], v[44:45]
	v_add_f32_e32 v80, v80, v150
	v_add_f32_e32 v80, v80, v151
	v_pk_mul_f32 v[152:153], v[46:47], v[46:47]
	v_add_f32_e32 v80, v80, v152
	v_add_f32_e32 v80, v80, v153
	v_pk_mul_f32 v[150:151], v[0:1], v[0:1]
	v_add_f32_e32 v80, v80, v150
	v_add_f32_e32 v80, v80, v151
	v_pk_mul_f32 v[152:153], v[2:3], v[2:3]
	v_add_f32_e32 v80, v80, v152
	v_add_f32_e32 v80, v80, v153
	v_pk_mul_f32 v[150:151], v[4:5], v[4:5]
	v_add_f32_e32 v80, v80, v150
	v_add_f32_e32 v80, v80, v151
	v_pk_mul_f32 v[152:153], v[6:7], v[6:7]
	v_add_f32_e32 v80, v80, v152
	v_add_f32_e32 v80, v80, v153
	v_pk_mul_f32 v[150:151], v[8:9], v[8:9]
	v_add_f32_e32 v80, v80, v150
	v_add_f32_e32 v80, v80, v151
	v_pk_mul_f32 v[152:153], v[10:11], v[10:11]
	v_add_f32_e32 v80, v80, v152
	v_add_f32_e32 v80, v80, v153
	v_pk_mul_f32 v[150:151], v[12:13], v[12:13]
	v_add_f32_e32 v80, v80, v150
	v_add_f32_e32 v80, v80, v151
	v_pk_mul_f32 v[152:153], v[14:15], v[14:15]
	v_add_f32_e32 v80, v80, v152
	v_add_f32_e32 v80, v80, v153
	ds_bpermute_b32 v81, v158, v80
	s_waitcnt lgkmcnt(0)
; DI float bflo(unsigned v) { return __uint_as_float(v << 16); }
; DI float bfhi(unsigned v) { return __uint_as_float(v & 0xffff0000u); }
; DI void attn_item(const P& p, int l, int item, char* smem) {
;     ...
;     const float rn = rsqrtf(ss * (1.0f / 128.0f) + 1e-5f) * (1.0f - lam_init);
;     const size_t tok = (size_t)b * SEQ + tq;
; #pragma unroll
;     for (int eb = 0; eb < 4; ++eb)
; #pragma unroll
;       for (int rq = 0; rq < 4; ++rq) {
;         const int e = 32 * eb + 8 * rq + 4 * g;
;         const uint2 gt = *(const uint2*)(p.AG + tok * 512 + h * 128 + e);
;         const float4 sg = *(const float4*)(p.subg + l * 128 + e);
;         const float o0 = O[eb][4 * rq + 0] * rn * sg.x * bflo(gt.x);
;         const float o1 = O[eb][4 * rq + 1] * rn * sg.y * bfhi(gt.x);
;         const float o2 = O[eb][4 * rq + 2] * rn * sg.z * bflo(gt.y);
;         const float o3 = O[eb][4 * rq + 3] * rn * sg.w * bfhi(gt.y);
;         uint2 ov; ov.x = pack2(o0, o1); ov.y = pack2(o2, o3);
;         *(uint2*)(p.Ya + tok * 512 + h * 128 + e) = ov;
	v_add_f32_e32 v80, v80, v81
	v_fmamk_f32 v80, v80, 0x3c000000, v210
	s_mov_b32 s6, 0x800000
	v_cmp_gt_f32_e32 vcc, s6, v80
	v_mul_f32_e32 v81, 0x4b800000, v80
	s_nop 0
	v_cndmask_b32_e32 v80, v80, v81, vcc
	v_rsq_f32_e32 v80, v80
	s_nop 0
	v_mul_f32_e32 v81, 0x45800000, v80
	v_cndmask_b32_e32 v80, v80, v81, vcc
	v_mul_f32_e32 v80, v220, v80
	v_pk_mul_f32 v[64:65], v[64:65], v[80:81] op_sel_hi:[1,0]
	v_pk_mul_f32 v[66:67], v[66:67], v[80:81] op_sel_hi:[1,0]
	ds_write_b128 v149, v[64:67] offset:0
	v_pk_mul_f32 v[68:69], v[68:69], v[80:81] op_sel_hi:[1,0]
	v_pk_mul_f32 v[70:71], v[70:71], v[80:81] op_sel_hi:[1,0]
	ds_write_b128 v149, v[68:71] offset:32
	v_pk_mul_f32 v[72:73], v[72:73], v[80:81] op_sel_hi:[1,0]
	v_pk_mul_f32 v[74:75], v[74:75], v[80:81] op_sel_hi:[1,0]
	ds_write_b128 v149, v[72:75] offset:64
	v_pk_mul_f32 v[76:77], v[76:77], v[80:81] op_sel_hi:[1,0]
	v_pk_mul_f32 v[78:79], v[78:79], v[80:81] op_sel_hi:[1,0]
	ds_write_b128 v149, v[76:79] offset:96
	v_pk_mul_f32 v[48:49], v[48:49], v[80:81] op_sel_hi:[1,0]
	v_pk_mul_f32 v[50:51], v[50:51], v[80:81] op_sel_hi:[1,0]
	ds_write_b128 v149, v[48:51] offset:128
	v_pk_mul_f32 v[52:53], v[52:53], v[80:81] op_sel_hi:[1,0]
	v_pk_mul_f32 v[54:55], v[54:55], v[80:81] op_sel_hi:[1,0]
	ds_write_b128 v149, v[52:55] offset:160
	v_pk_mul_f32 v[56:57], v[56:57], v[80:81] op_sel_hi:[1,0]
	v_pk_mul_f32 v[58:59], v[58:59], v[80:81] op_sel_hi:[1,0]
	ds_write_b128 v149, v[56:59] offset:192
	v_pk_mul_f32 v[60:61], v[60:61], v[80:81] op_sel_hi:[1,0]
	v_pk_mul_f32 v[62:63], v[62:63], v[80:81] op_sel_hi:[1,0]
	ds_write_b128 v149, v[60:63] offset:224
	v_pk_mul_f32 v[32:33], v[32:33], v[80:81] op_sel_hi:[1,0]
	v_pk_mul_f32 v[34:35], v[34:35], v[80:81] op_sel_hi:[1,0]
	ds_write_b128 v149, v[32:35] offset:256
	v_pk_mul_f32 v[36:37], v[36:37], v[80:81] op_sel_hi:[1,0]
	v_pk_mul_f32 v[38:39], v[38:39], v[80:81] op_sel_hi:[1,0]
	ds_write_b128 v149, v[36:39] offset:288
	v_pk_mul_f32 v[40:41], v[40:41], v[80:81] op_sel_hi:[1,0]
	v_pk_mul_f32 v[42:43], v[42:43], v[80:81] op_sel_hi:[1,0]
	ds_write_b128 v149, v[40:43] offset:320
	v_pk_mul_f32 v[44:45], v[44:45], v[80:81] op_sel_hi:[1,0]
	v_pk_mul_f32 v[46:47], v[46:47], v[80:81] op_sel_hi:[1,0]
	ds_write_b128 v149, v[44:47] offset:352
	v_pk_mul_f32 v[0:1], v[0:1], v[80:81] op_sel_hi:[1,0]
	v_pk_mul_f32 v[2:3], v[2:3], v[80:81] op_sel_hi:[1,0]
	ds_write_b128 v149, v[0:3] offset:384
	v_pk_mul_f32 v[4:5], v[4:5], v[80:81] op_sel_hi:[1,0]
	v_pk_mul_f32 v[6:7], v[6:7], v[80:81] op_sel_hi:[1,0]
	ds_write_b128 v149, v[4:7] offset:416
	v_pk_mul_f32 v[8:9], v[8:9], v[80:81] op_sel_hi:[1,0]
	v_pk_mul_f32 v[10:11], v[10:11], v[80:81] op_sel_hi:[1,0]
	ds_write_b128 v149, v[8:11] offset:448
	v_pk_mul_f32 v[12:13], v[12:13], v[80:81] op_sel_hi:[1,0]
	v_pk_mul_f32 v[14:15], v[14:15], v[80:81] op_sel_hi:[1,0]
	ds_write_b128 v149, v[12:15] offset:480
	ds_read_b128 v[0:3], v146 offset:0
	ds_read_b128 v[4:7], v146 offset:16
	ds_read_b128 v[8:11], v146 offset:2112
	ds_read_b128 v[12:15], v146 offset:2128
	ds_read_b128 v[16:19], v146 offset:4224
	ds_read_b128 v[20:23], v146 offset:4240
	ds_read_b128 v[24:27], v146 offset:6336
	ds_read_b128 v[28:31], v146 offset:6352
	ds_read_b128 v[32:35], v146 offset:8448
	ds_read_b128 v[36:39], v146 offset:8464
	ds_read_b128 v[40:43], v146 offset:10560
	ds_read_b128 v[44:47], v146 offset:10576
	ds_read_b128 v[48:51], v146 offset:12672
	ds_read_b128 v[52:55], v146 offset:12688
	ds_read_b128 v[56:59], v146 offset:14784
	ds_read_b128 v[60:63], v146 offset:14800
	s_waitcnt vmcnt(7) lgkmcnt(14)
	v_pk_mul_f32 v[0:1], v[100:101], v[0:1]
	v_pk_mul_f32 v[2:3], v[102:103], v[2:3]
	v_pk_mul_f32 v[4:5], v[104:105], v[4:5]
	v_pk_mul_f32 v[6:7], v[106:107], v[6:7]
	v_lshlrev_b32_e32 v64, 16, v228
	v_and_b32_e32 v65, 0xffff0000, v228
	v_lshlrev_b32_e32 v66, 16, v229
	v_and_b32_e32 v67, 0xffff0000, v229
	v_lshlrev_b32_e32 v68, 16, v230
	v_and_b32_e32 v69, 0xffff0000, v230
	v_lshlrev_b32_e32 v70, 16, v231
	v_and_b32_e32 v71, 0xffff0000, v231
	v_pk_mul_f32 v[0:1], v[0:1], v[64:65]
	v_pk_mul_f32 v[2:3], v[2:3], v[66:67]
	v_pk_mul_f32 v[4:5], v[4:5], v[68:69]
	v_pk_mul_f32 v[6:7], v[6:7], v[70:71]
	v_cvt_pk_bf16_f32 v72, v0, v1
	v_cvt_pk_bf16_f32 v73, v2, v3
	v_cvt_pk_bf16_f32 v74, v4, v5
	v_cvt_pk_bf16_f32 v75, v6, v7
	global_store_dwordx4 v147, v[72:75], s[46:47]
	v_add_u32_e32 v147, 0x1000, v147
	s_waitcnt vmcnt(7) lgkmcnt(12)
	v_pk_mul_f32 v[8:9], v[100:101], v[8:9]
	v_pk_mul_f32 v[10:11], v[102:103], v[10:11]
	v_pk_mul_f32 v[12:13], v[104:105], v[12:13]
	v_pk_mul_f32 v[14:15], v[106:107], v[14:15]
	v_lshlrev_b32_e32 v64, 16, v232
	v_and_b32_e32 v65, 0xffff0000, v232
	v_lshlrev_b32_e32 v66, 16, v233
	v_and_b32_e32 v67, 0xffff0000, v233
	v_lshlrev_b32_e32 v68, 16, v234
	v_and_b32_e32 v69, 0xffff0000, v234
	v_lshlrev_b32_e32 v70, 16, v235
	v_and_b32_e32 v71, 0xffff0000, v235
	v_pk_mul_f32 v[8:9], v[8:9], v[64:65]
	v_pk_mul_f32 v[10:11], v[10:11], v[66:67]
	v_pk_mul_f32 v[12:13], v[12:13], v[68:69]
	v_pk_mul_f32 v[14:15], v[14:15], v[70:71]
	v_cvt_pk_bf16_f32 v76, v8, v9
	v_cvt_pk_bf16_f32 v77, v10, v11
	v_cvt_pk_bf16_f32 v78, v12, v13
	v_cvt_pk_bf16_f32 v79, v14, v15
	global_store_dwordx4 v147, v[76:79], s[46:47]
	v_add_u32_e32 v147, 0x1000, v147
	s_waitcnt vmcnt(7) lgkmcnt(10)
; DI float bflo(unsigned v) { return __uint_as_float(v << 16); }
; DI float bfhi(unsigned v) { return __uint_as_float(v & 0xffff0000u); }
; DI void attn_item(const P& p, int l, int item, char* smem) {
;     ...
; #pragma unroll
;     for (int eb = 0; eb < 4; ++eb)
; #pragma unroll
;       for (int rq = 0; rq < 4; ++rq) {
;         const int e = 32 * eb + 8 * rq + 4 * g;
;         const uint2 gt = *(const uint2*)(p.AG + tok * 512 + h * 128 + e);
;         const float4 sg = *(const float4*)(p.subg + l * 128 + e);
;         const float o0 = O[eb][4 * rq + 0] * rn * sg.x * bflo(gt.x);
;         const float o1 = O[eb][4 * rq + 1] * rn * sg.y * bfhi(gt.x);
;         const float o2 = O[eb][4 * rq + 2] * rn * sg.z * bflo(gt.y);
;         const float o3 = O[eb][4 * rq + 3] * rn * sg.w * bfhi(gt.y);
;         uint2 ov; ov.x = pack2(o0, o1); ov.y = pack2(o2, o3);
;         *(uint2*)(p.Ya + tok * 512 + h * 128 + e) = ov;
	v_pk_mul_f32 v[16:17], v[100:101], v[16:17]
	v_pk_mul_f32 v[18:19], v[102:103], v[18:19]
	v_pk_mul_f32 v[20:21], v[104:105], v[20:21]
	v_pk_mul_f32 v[22:23], v[106:107], v[22:23]
	v_lshlrev_b32_e32 v64, 16, v236
	v_and_b32_e32 v65, 0xffff0000, v236
	v_lshlrev_b32_e32 v66, 16, v237
	v_and_b32_e32 v67, 0xffff0000, v237
	v_lshlrev_b32_e32 v68, 16, v238
	v_and_b32_e32 v69, 0xffff0000, v238
	v_lshlrev_b32_e32 v70, 16, v239
	v_and_b32_e32 v71, 0xffff0000, v239
	v_pk_mul_f32 v[16:17], v[16:17], v[64:65]
	v_pk_mul_f32 v[18:19], v[18:19], v[66:67]
	v_pk_mul_f32 v[20:21], v[20:21], v[68:69]
	v_pk_mul_f32 v[22:23], v[22:23], v[70:71]
	v_cvt_pk_bf16_f32 v72, v16, v17
	v_cvt_pk_bf16_f32 v73, v18, v19
	v_cvt_pk_bf16_f32 v74, v20, v21
	v_cvt_pk_bf16_f32 v75, v22, v23
	global_store_dwordx4 v147, v[72:75], s[46:47]
	v_add_u32_e32 v147, 0x1000, v147
	s_waitcnt vmcnt(7) lgkmcnt(8)
	v_pk_mul_f32 v[24:25], v[100:101], v[24:25]
	v_pk_mul_f32 v[26:27], v[102:103], v[26:27]
	v_pk_mul_f32 v[28:29], v[104:105], v[28:29]
	v_pk_mul_f32 v[30:31], v[106:107], v[30:31]
	v_lshlrev_b32_e32 v64, 16, v240
	v_and_b32_e32 v65, 0xffff0000, v240
	v_lshlrev_b32_e32 v66, 16, v241
	v_and_b32_e32 v67, 0xffff0000, v241
	v_lshlrev_b32_e32 v68, 16, v242
	v_and_b32_e32 v69, 0xffff0000, v242
	v_lshlrev_b32_e32 v70, 16, v243
	v_and_b32_e32 v71, 0xffff0000, v243
	v_pk_mul_f32 v[24:25], v[24:25], v[64:65]
	v_pk_mul_f32 v[26:27], v[26:27], v[66:67]
	v_pk_mul_f32 v[28:29], v[28:29], v[68:69]
	v_pk_mul_f32 v[30:31], v[30:31], v[70:71]
	v_cvt_pk_bf16_f32 v76, v24, v25
	v_cvt_pk_bf16_f32 v77, v26, v27
	v_cvt_pk_bf16_f32 v78, v28, v29
	v_cvt_pk_bf16_f32 v79, v30, v31
	global_store_dwordx4 v147, v[76:79], s[46:47]
	v_add_u32_e32 v147, 0x1000, v147
	s_waitcnt vmcnt(7) lgkmcnt(6)
	v_pk_mul_f32 v[32:33], v[100:101], v[32:33]
	v_pk_mul_f32 v[34:35], v[102:103], v[34:35]
	v_pk_mul_f32 v[36:37], v[104:105], v[36:37]
	v_pk_mul_f32 v[38:39], v[106:107], v[38:39]
	v_lshlrev_b32_e32 v64, 16, v84
	v_and_b32_e32 v65, 0xffff0000, v84
	v_lshlrev_b32_e32 v66, 16, v85
	v_and_b32_e32 v67, 0xffff0000, v85
	v_lshlrev_b32_e32 v68, 16, v86
	v_and_b32_e32 v69, 0xffff0000, v86
	v_lshlrev_b32_e32 v70, 16, v87
	v_and_b32_e32 v71, 0xffff0000, v87
	v_pk_mul_f32 v[32:33], v[32:33], v[64:65]
	v_pk_mul_f32 v[34:35], v[34:35], v[66:67]
	v_pk_mul_f32 v[36:37], v[36:37], v[68:69]
	v_pk_mul_f32 v[38:39], v[38:39], v[70:71]
	v_cvt_pk_bf16_f32 v72, v32, v33
	v_cvt_pk_bf16_f32 v73, v34, v35
	v_cvt_pk_bf16_f32 v74, v36, v37
	v_cvt_pk_bf16_f32 v75, v38, v39
	global_store_dwordx4 v147, v[72:75], s[46:47]
	v_add_u32_e32 v147, 0x1000, v147
	s_waitcnt vmcnt(7) lgkmcnt(4)
	v_pk_mul_f32 v[40:41], v[100:101], v[40:41]
	v_pk_mul_f32 v[42:43], v[102:103], v[42:43]
	v_pk_mul_f32 v[44:45], v[104:105], v[44:45]
	v_pk_mul_f32 v[46:47], v[106:107], v[46:47]
	v_lshlrev_b32_e32 v64, 16, v88
	v_and_b32_e32 v65, 0xffff0000, v88
	v_lshlrev_b32_e32 v66, 16, v89
	v_and_b32_e32 v67, 0xffff0000, v89
	v_lshlrev_b32_e32 v68, 16, v90
	v_and_b32_e32 v69, 0xffff0000, v90
	v_lshlrev_b32_e32 v70, 16, v91
	v_and_b32_e32 v71, 0xffff0000, v91
	v_pk_mul_f32 v[40:41], v[40:41], v[64:65]
	v_pk_mul_f32 v[42:43], v[42:43], v[66:67]
	v_pk_mul_f32 v[44:45], v[44:45], v[68:69]
	v_pk_mul_f32 v[46:47], v[46:47], v[70:71]
	v_cvt_pk_bf16_f32 v76, v40, v41
	v_cvt_pk_bf16_f32 v77, v42, v43
	v_cvt_pk_bf16_f32 v78, v44, v45
	v_cvt_pk_bf16_f32 v79, v46, v47
	global_store_dwordx4 v147, v[76:79], s[46:47]
	v_add_u32_e32 v147, 0x1000, v147
	s_waitcnt vmcnt(7) lgkmcnt(2)
	v_pk_mul_f32 v[48:49], v[100:101], v[48:49]
	v_pk_mul_f32 v[50:51], v[102:103], v[50:51]
	v_pk_mul_f32 v[52:53], v[104:105], v[52:53]
	v_pk_mul_f32 v[54:55], v[106:107], v[54:55]
	v_lshlrev_b32_e32 v64, 16, v92
	v_and_b32_e32 v65, 0xffff0000, v92
	v_lshlrev_b32_e32 v66, 16, v93
	v_and_b32_e32 v67, 0xffff0000, v93
	v_lshlrev_b32_e32 v68, 16, v94
	v_and_b32_e32 v69, 0xffff0000, v94
	v_lshlrev_b32_e32 v70, 16, v95
	v_and_b32_e32 v71, 0xffff0000, v95
	v_pk_mul_f32 v[48:49], v[48:49], v[64:65]
	v_pk_mul_f32 v[50:51], v[50:51], v[66:67]
	v_pk_mul_f32 v[52:53], v[52:53], v[68:69]
	v_pk_mul_f32 v[54:55], v[54:55], v[70:71]
	v_cvt_pk_bf16_f32 v72, v48, v49
	v_cvt_pk_bf16_f32 v73, v50, v51
	v_cvt_pk_bf16_f32 v74, v52, v53
	v_cvt_pk_bf16_f32 v75, v54, v55
	global_store_dwordx4 v147, v[72:75], s[46:47]
	v_add_u32_e32 v147, 0x1000, v147
	s_waitcnt vmcnt(7) lgkmcnt(0)
	v_pk_mul_f32 v[56:57], v[100:101], v[56:57]
	v_pk_mul_f32 v[58:59], v[102:103], v[58:59]
	v_pk_mul_f32 v[60:61], v[104:105], v[60:61]
	v_pk_mul_f32 v[62:63], v[106:107], v[62:63]
	v_lshlrev_b32_e32 v64, 16, v96
	v_and_b32_e32 v65, 0xffff0000, v96
	v_lshlrev_b32_e32 v66, 16, v97
	v_and_b32_e32 v67, 0xffff0000, v97
	v_lshlrev_b32_e32 v68, 16, v98
	v_and_b32_e32 v69, 0xffff0000, v98
	v_lshlrev_b32_e32 v70, 16, v99
	v_and_b32_e32 v71, 0xffff0000, v99
	v_pk_mul_f32 v[56:57], v[56:57], v[64:65]
	v_pk_mul_f32 v[58:59], v[58:59], v[66:67]
	v_pk_mul_f32 v[60:61], v[60:61], v[68:69]
	v_pk_mul_f32 v[62:63], v[62:63], v[70:71]
	v_cvt_pk_bf16_f32 v76, v56, v57
	v_cvt_pk_bf16_f32 v77, v58, v59
	v_cvt_pk_bf16_f32 v78, v60, v61
	v_cvt_pk_bf16_f32 v79, v62, v63
	global_store_dwordx4 v147, v[76:79], s[46:47]
